# MLA loop: V fragment reads issued behind the first five K fragment reads (on top of the diff-loop changes)
# speedup vs baseline: 1.0011x; 1.0011x over previous
.LBB0_190:
	s_bitcmp1_b32 s1, 0
	s_cselect_b32 s0, 0x5400, 0
	s_add_i32 s0, s0, 0
	v_add_u32_e32 v100, s0, v174
	v_add3_u32 v100, v100, v175, v176
	v_add_u32_e32 v184, v100, v177
	v_add_u32_e32 v183, v100, v178
	v_add_u32_e32 v182, v100, v179
	v_add_u32_e32 v181, v100, v180
	v_add3_u32 v185, s0, v192, v159
	ds_read_b128 v[116:119], v185
	ds_read_b128 v[186:189], v185 offset:64
	s_waitcnt lgkmcnt(1)
	v_mfma_f32_16x16x32_bf16 v[120:123], v[116:119], v[12:15], v[36:39]
	ds_read_b128 v[124:127], v185 offset:832
	ds_read_b128 v[132:135], v185 offset:6656
	ds_read_b128 v[140:143], v185 offset:7488
	ds_read_b64_tr_b16 v[112:113], v184 offset:13312
	ds_read_b64_tr_b16 v[114:115], v184 offset:13824
	ds_read_b64_tr_b16 v[108:109], v183 offset:13312
	ds_read_b64_tr_b16 v[110:111], v183 offset:13824
	ds_read_b64_tr_b16 v[104:105], v182 offset:13312
	ds_read_b64_tr_b16 v[106:107], v182 offset:13824
	ds_read_b64_tr_b16 v[100:101], v181 offset:13312
	ds_read_b64_tr_b16 v[102:103], v181 offset:13824
	v_mfma_f32_16x16x32_bf16 v[116:119], v[116:119], v[20:23], v[48:51]
	s_andn2_b32 s0, 1, s1
	s_mulk_i32 s0, 0x5400
	s_add_i32 s0, s0, 0
	s_waitcnt lgkmcnt(11)
	v_mfma_f32_16x16x32_bf16 v[120:123], v[186:189], v[16:19], v[120:123]
	s_add_i32 s10, s1, 1
	v_mfma_f32_16x16x32_bf16 v[116:119], v[186:189], v[24:27], v[116:119]
	ds_read_b128 v[186:189], v185 offset:896
	s_waitcnt lgkmcnt(11)
	v_mfma_f32_16x16x32_bf16 v[128:131], v[124:127], v[12:15], v[36:39]
	v_mfma_f32_16x16x32_bf16 v[124:127], v[124:127], v[20:23], v[48:51]
	s_waitcnt lgkmcnt(0)
	v_mfma_f32_16x16x32_bf16 v[128:131], v[186:189], v[16:19], v[128:131]
	v_mfma_f32_16x16x32_bf16 v[124:127], v[186:189], v[24:27], v[124:127]
	ds_read_b128 v[186:189], v185 offset:6720
	v_mfma_f32_16x16x32_bf16 v[136:139], v[132:135], v[12:15], v[36:39]
	v_mfma_f32_16x16x32_bf16 v[132:135], v[132:135], v[20:23], v[48:51]
	s_waitcnt lgkmcnt(0)
	v_mfma_f32_16x16x32_bf16 v[194:197], v[186:189], v[16:19], v[136:139]
	v_mfma_f32_16x16x32_bf16 v[186:189], v[186:189], v[24:27], v[132:135]
	s_nop 4
	ds_read_b128 v[132:135], v185 offset:7552
	v_mfma_f32_16x16x32_bf16 v[144:147], v[140:143], v[12:15], v[36:39]
	v_mfma_f32_16x16x32_bf16 v[140:143], v[140:143], v[20:23], v[48:51]
	s_waitcnt lgkmcnt(0)
	v_mfma_f32_16x16x32_bf16 v[144:147], v[132:135], v[16:19], v[144:147]
	v_mfma_f32_16x16x32_bf16 v[202:205], v[132:135], v[24:27], v[140:143]
	ds_read_b128 v[132:135], v185 offset:128
	s_waitcnt lgkmcnt(0)
	v_mfma_f32_16x16x32_bf16 v[136:139], v[132:135], v[0:3], v[120:123]
	v_mfma_f32_16x16x32_bf16 v[120:123], v[132:135], v[4:7], v[116:119]
	s_nop 2
	ds_read_b128 v[116:119], v185 offset:960
	s_waitcnt lgkmcnt(0)
	v_mfma_f32_16x16x32_bf16 v[132:135], v[116:119], v[0:3], v[128:131]
	s_nop 2
	ds_read_b128 v[128:131], v185 offset:7616
	v_mfma_f32_16x16x32_bf16 v[116:119], v[116:119], v[4:7], v[124:127]
	s_nop 2
	ds_read_b128 v[124:127], v185 offset:6784
	v_add3_u32 v185, s0, v151, v155
	s_waitcnt vmcnt(2)
	ds_write_b128 v185, v[8:11]
	v_add3_u32 v8, s0, v157, v170
	s_waitcnt vmcnt(0)
	ds_write_b128 v8, v[28:31]
	v_add_u32_e32 v8, s0, v171
	s_add_i32 s0, s1, 3
	s_min_u32 s0, s0, s83
	v_add3_u32 v8, v8, v173, v172
	s_lshl_b32 s0, s0, 6
	ds_write_b128 v8, v[32:35] offset:13312
	v_add_u32_e32 v8, s0, v154
	v_add_u32_e32 v28, s0, v156
	s_add_i32 s0, s1, 2
	v_ashrrev_i32_e32 v9, 31, v8
	v_ashrrev_i32_e32 v29, 31, v28
	s_min_u32 s0, s0, s83
	v_lshlrev_b64 v[10:11], 11, v[8:9]
	v_lshlrev_b64 v[8:9], 6, v[8:9]
	v_lshlrev_b64 v[30:31], 11, v[28:29]
	v_lshlrev_b64 v[28:29], 6, v[28:29]
	v_lshl_add_u32 v32, s0, 6, v158
	v_lshl_add_u64 v[8:9], v[162:163], 0, v[8:9]
	v_lshl_add_u64 v[28:29], v[166:167], 0, v[28:29]
	v_ashrrev_i32_e32 v33, 31, v32
	v_lshl_add_u64 v[10:11], v[164:165], 0, v[10:11]
	v_lshl_add_u64 v[8:9], v[8:9], 0, s[58:59]
	v_lshl_add_u64 v[30:31], v[168:169], 0, v[30:31]
	v_lshl_add_u64 v[28:29], v[28:29], 0, s[58:59]
	v_lshlrev_b64 v[32:33], 11, v[32:33]
	v_cndmask_b32_e64 v9, v9, v11, s[6:7]
	v_cndmask_b32_e64 v8, v8, v10, s[6:7]
	v_cndmask_b32_e64 v29, v29, v31, s[8:9]
	v_cndmask_b32_e64 v28, v28, v30, s[8:9]
	v_lshl_add_u64 v[32:33], v[160:161], 0, v[32:33]
	global_load_dwordx4 v[8:11], v[8:9], off
	s_waitcnt lgkmcnt(3)
	v_mfma_f32_16x16x32_bf16 v[140:143], v[124:127], v[0:3], v[194:197]
	global_load_dwordx4 v[28:31], v[28:29], off
	s_cmp_ge_u32 s10, s82
	global_load_dwordx4 v[32:35], v[32:33], off offset:128
	v_mfma_f32_16x16x32_bf16 v[124:127], v[124:127], v[4:7], v[186:189]
	v_mfma_f32_16x16x32_bf16 v[144:147], v[128:131], v[0:3], v[144:147]
	v_mfma_f32_16x16x32_bf16 v[128:131], v[128:131], v[4:7], v[202:205]
	s_cbranch_scc1 .LBB0_196
	s_cmp_lg_u32 s1, 0
	s_cselect_b64 s[0:1], -1, 0
	s_and_b32 s11, s10, 3
	s_cmp_lg_u32 s11, 0
	s_cselect_b64 s[14:15], -1, 0
	s_and_b64 s[0:1], s[0:1], s[14:15]
	s_and_b64 vcc, exec, s[0:1]
	s_cbranch_vccnz .LBB0_196
	v_max_f32_e32 v185, v137, v137
	v_max_f32_e32 v186, v136, v136
	v_max_f32_e32 v185, v186, v185
	v_max3_f32 v185, v185, v138, v139
	v_max3_f32 v185, v185, v132, v133
	v_max3_f32 v185, v185, v134, v135
	v_max3_f32 v185, v185, v140, v141
	v_max3_f32 v185, v185, v142, v143
	v_max3_f32 v185, v185, v144, v145
	v_max3_f32 v185, v185, v146, v147
	v_mov_b32_e32 v186, v185
	s_nop 1
	v_permlane16_swap_b32_e32 v185, v186
	v_max_f32_e32 v186, v186, v186
	v_max_f32_e32 v185, v185, v185
	v_max_f32_e32 v185, v185, v186
	v_mov_b32_e32 v186, v185
	s_nop 1
	v_permlane32_swap_b32_e32 v185, v186
	v_max_f32_e32 v186, v186, v186
	v_max_f32_e32 v185, v185, v185
	v_max_f32_e32 v185, v185, v186
	v_cmp_lt_f32_e32 vcc, s44, v185
	s_cbranch_vccz .LBB0_194
	s_nop 0
	v_cndmask_b32_e32 v185, 0, v185, vcc
	v_exp_f32_e64 v186, -v185
	v_lshlrev_b32_e32 v188, 16, v56
	v_and_b32_e32 v189, 0xffff0000, v56
	v_sub_f32_e32 v139, v139, v185
	v_pk_mul_f32 v[188:189], v[186:187], v[188:189] op_sel_hi:[0,1]
	v_cvt_pk_bf16_f32 v56, v188, v189
	v_lshlrev_b32_e32 v188, 16, v57
	v_and_b32_e32 v189, 0xffff0000, v57
	v_pk_mul_f32 v[188:189], v[186:187], v[188:189] op_sel_hi:[0,1]
	v_cvt_pk_bf16_f32 v57, v188, v189
	v_lshlrev_b32_e32 v188, 16, v58
	v_and_b32_e32 v189, 0xffff0000, v58
	v_pk_mul_f32 v[188:189], v[186:187], v[188:189] op_sel_hi:[0,1]
	v_cvt_pk_bf16_f32 v58, v188, v189
	v_lshlrev_b32_e32 v188, 16, v59
	v_and_b32_e32 v189, 0xffff0000, v59
	v_pk_mul_f32 v[188:189], v[186:187], v[188:189] op_sel_hi:[0,1]
	v_cvt_pk_bf16_f32 v59, v188, v189
	v_lshlrev_b32_e32 v188, 16, v52
	v_and_b32_e32 v189, 0xffff0000, v52
	v_pk_mul_f32 v[188:189], v[186:187], v[188:189] op_sel_hi:[0,1]
	v_cvt_pk_bf16_f32 v52, v188, v189
	v_lshlrev_b32_e32 v188, 16, v53
	v_and_b32_e32 v189, 0xffff0000, v53
	v_pk_mul_f32 v[188:189], v[186:187], v[188:189] op_sel_hi:[0,1]
	v_cvt_pk_bf16_f32 v53, v188, v189
	v_lshlrev_b32_e32 v188, 16, v54
	v_and_b32_e32 v189, 0xffff0000, v54
	v_pk_mul_f32 v[188:189], v[186:187], v[188:189] op_sel_hi:[0,1]
	v_cvt_pk_bf16_f32 v54, v188, v189
	v_lshlrev_b32_e32 v188, 16, v55
	v_and_b32_e32 v189, 0xffff0000, v55
	v_pk_mul_f32 v[78:79], v[78:79], v[186:187] op_sel_hi:[1,0]
	v_pk_mul_f32 v[76:77], v[76:77], v[186:187] op_sel_hi:[1,0]
	v_pk_mul_f32 v[98:99], v[98:99], v[186:187] op_sel_hi:[1,0]
	v_pk_mul_f32 v[96:97], v[96:97], v[186:187] op_sel_hi:[1,0]
	v_pk_mul_f32 v[94:95], v[94:95], v[186:187] op_sel_hi:[1,0]
	v_pk_mul_f32 v[92:93], v[92:93], v[186:187] op_sel_hi:[1,0]
	v_pk_mul_f32 v[86:87], v[86:87], v[186:187] op_sel_hi:[1,0]
	v_pk_mul_f32 v[84:85], v[84:85], v[186:187] op_sel_hi:[1,0]
	v_pk_mul_f32 v[42:43], v[42:43], v[186:187] op_sel_hi:[1,0]
	v_pk_mul_f32 v[40:41], v[40:41], v[186:187] op_sel_hi:[1,0]
	v_pk_mul_f32 v[186:187], v[186:187], v[188:189] op_sel_hi:[0,1]
	v_sub_f32_e32 v138, v138, v185
	v_sub_f32_e32 v137, v137, v185
	v_sub_f32_e32 v136, v136, v185
	v_sub_f32_e32 v135, v135, v185
	v_sub_f32_e32 v134, v134, v185
	v_sub_f32_e32 v133, v133, v185
	v_sub_f32_e32 v132, v132, v185
	v_sub_f32_e32 v143, v143, v185
	v_sub_f32_e32 v142, v142, v185
	v_sub_f32_e32 v141, v141, v185
	v_sub_f32_e32 v140, v140, v185
	v_sub_f32_e32 v147, v147, v185
	v_sub_f32_e32 v146, v146, v185
	v_sub_f32_e32 v145, v145, v185
	v_sub_f32_e32 v144, v144, v185
	v_cvt_pk_bf16_f32 v55, v186, v187
	v_sub_f32_e32 v39, v39, v185
	v_sub_f32_e32 v38, v38, v185
	v_sub_f32_e32 v37, v37, v185
	v_sub_f32_e32 v36, v36, v185
